# hgrn pass-2 state prefix scan: 64 loads per step issued at once (was 4 dependent rounds per step)
# speedup vs baseline: 1.0089x; 1.0069x over previous
.LBB0_287:
	s_and_b64 vcc, s[42:43], exec
	s_cselect_b32 s81, s5, s20
	s_add_i32 vcc_lo, s4, s81
	s_ashr_i32 vcc_hi, vcc_lo, 31
	s_lshl_b64 vcc, vcc, 16
	s_add_u32 vcc_lo, s52, vcc_lo
	v_bfe_u32 v8, v236, 5, 1
	s_addc_u32 vcc_hi, s53, vcc_hi
	v_lshlrev_b32_e32 v0, 11, v8
	v_lshl_add_u64 v[2:3], vcc, 0, v[0:1]
	v_ashrrev_i32_e32 v0, 1, v236
	v_and_b32_e32 v4, 0xffffffe0, v0
	v_and_b32_e32 v6, 31, v236
	v_ashrrev_i32_e32 v5, 31, v4
	v_lshl_add_u64 v[2:3], v[4:5], 2, v[2:3]
	v_lshlrev_b32_e32 v0, 2, v6
	v_lshl_add_u64 v[6:7], v[2:3], 0, v[0:1]
	v_lshl_add_u32 v0, v8, 4, s21
	global_load_dword v80, v[6:7], off
	global_load_dword v81, v[6:7], off offset:512
	global_load_dword v82, v[6:7], off offset:1024
	global_load_dword v83, v[6:7], off offset:1536
	v_lshl_add_u64 v[6:7], v[6:7], 0, s[8:9]
	global_load_dword v84, v[6:7], off
	global_load_dword v85, v[6:7], off offset:512
	global_load_dword v86, v[6:7], off offset:1024
	global_load_dword v87, v[6:7], off offset:1536
	v_lshl_add_u64 v[6:7], v[6:7], 0, s[8:9]
	global_load_dword v88, v[6:7], off
	global_load_dword v89, v[6:7], off offset:512
	global_load_dword v90, v[6:7], off offset:1024
	global_load_dword v91, v[6:7], off offset:1536
	v_lshl_add_u64 v[6:7], v[6:7], 0, s[8:9]
	global_load_dword v92, v[6:7], off
	global_load_dword v93, v[6:7], off offset:512
	global_load_dword v94, v[6:7], off offset:1024
	global_load_dword v95, v[6:7], off offset:1536
	v_lshl_add_u64 v[6:7], v[6:7], 0, s[8:9]
	global_load_dword v96, v[6:7], off
	global_load_dword v97, v[6:7], off offset:512
	global_load_dword v98, v[6:7], off offset:1024
	global_load_dword v99, v[6:7], off offset:1536
	v_lshl_add_u64 v[6:7], v[6:7], 0, s[8:9]
	global_load_dword v100, v[6:7], off
	global_load_dword v101, v[6:7], off offset:512
	global_load_dword v102, v[6:7], off offset:1024
	global_load_dword v103, v[6:7], off offset:1536
	v_lshl_add_u64 v[6:7], v[6:7], 0, s[8:9]
	global_load_dword v104, v[6:7], off
	global_load_dword v105, v[6:7], off offset:512
	global_load_dword v106, v[6:7], off offset:1024
	global_load_dword v107, v[6:7], off offset:1536
	v_lshl_add_u64 v[6:7], v[6:7], 0, s[8:9]
	global_load_dword v108, v[6:7], off
	global_load_dword v109, v[6:7], off offset:512
	global_load_dword v110, v[6:7], off offset:1024
	global_load_dword v111, v[6:7], off offset:1536
	v_lshl_add_u64 v[6:7], v[6:7], 0, s[8:9]
	global_load_dword v112, v[6:7], off
	global_load_dword v113, v[6:7], off offset:512
	global_load_dword v114, v[6:7], off offset:1024
	global_load_dword v115, v[6:7], off offset:1536
	v_lshl_add_u64 v[6:7], v[6:7], 0, s[8:9]
	global_load_dword v116, v[6:7], off
	global_load_dword v117, v[6:7], off offset:512
	global_load_dword v118, v[6:7], off offset:1024
	global_load_dword v119, v[6:7], off offset:1536
	v_lshl_add_u64 v[6:7], v[6:7], 0, s[8:9]
	global_load_dword v120, v[6:7], off
	global_load_dword v121, v[6:7], off offset:512
	global_load_dword v122, v[6:7], off offset:1024
	global_load_dword v123, v[6:7], off offset:1536
	v_lshl_add_u64 v[6:7], v[6:7], 0, s[8:9]
	global_load_dword v124, v[6:7], off
	global_load_dword v125, v[6:7], off offset:512
	global_load_dword v126, v[6:7], off offset:1024
	global_load_dword v127, v[6:7], off offset:1536
	v_lshl_add_u64 v[6:7], v[6:7], 0, s[8:9]
	global_load_dword v128, v[6:7], off
	global_load_dword v129, v[6:7], off offset:512
	global_load_dword v130, v[6:7], off offset:1024
	global_load_dword v131, v[6:7], off offset:1536
	v_lshl_add_u64 v[6:7], v[6:7], 0, s[8:9]
	global_load_dword v132, v[6:7], off
	global_load_dword v133, v[6:7], off offset:512
	global_load_dword v134, v[6:7], off offset:1024
	global_load_dword v135, v[6:7], off offset:1536
	v_lshl_add_u64 v[6:7], v[6:7], 0, s[8:9]
	global_load_dword v136, v[6:7], off
	global_load_dword v137, v[6:7], off offset:512
	global_load_dword v138, v[6:7], off offset:1024
	global_load_dword v139, v[6:7], off offset:1536
	v_lshl_add_u64 v[6:7], v[6:7], 0, s[8:9]
	global_load_dword v140, v[6:7], off
	global_load_dword v141, v[6:7], off offset:512
	global_load_dword v142, v[6:7], off offset:1024
	global_load_dword v143, v[6:7], off offset:1536
	s_add_i32 s5, s5, 1
	s_add_i32 s20, s20, -1
	ds_read_b128 v[2:5], v0
	ds_read_b128 v[8:11], v0 offset:32
	ds_read_b128 v[12:15], v0 offset:64
	ds_read_b128 v[206:209], v0 offset:96
	s_waitcnt vmcnt(48) lgkmcnt(0)
	v_pk_fma_f32 v[16:17], v[16:17], v[2:3], v[80:81]
	v_pk_fma_f32 v[18:19], v[18:19], v[4:5], v[82:83]
	v_pk_fma_f32 v[20:21], v[20:21], v[8:9], v[84:85]
	v_pk_fma_f32 v[22:23], v[22:23], v[10:11], v[86:87]
	v_pk_fma_f32 v[24:25], v[24:25], v[12:13], v[88:89]
	v_pk_fma_f32 v[26:27], v[26:27], v[14:15], v[90:91]
	v_pk_fma_f32 v[28:29], v[28:29], v[206:207], v[92:93]
	v_pk_fma_f32 v[30:31], v[30:31], v[208:209], v[94:95]
	ds_read_b128 v[2:5], v0 offset:128
	ds_read_b128 v[8:11], v0 offset:160
	ds_read_b128 v[12:15], v0 offset:192
	ds_read_b128 v[206:209], v0 offset:224
	s_waitcnt vmcnt(32) lgkmcnt(0)
	v_pk_fma_f32 v[32:33], v[32:33], v[2:3], v[96:97]
	v_pk_fma_f32 v[34:35], v[34:35], v[4:5], v[98:99]
	v_pk_fma_f32 v[36:37], v[36:37], v[8:9], v[100:101]
	v_pk_fma_f32 v[38:39], v[38:39], v[10:11], v[102:103]
	v_pk_fma_f32 v[40:41], v[40:41], v[12:13], v[104:105]
	v_pk_fma_f32 v[42:43], v[42:43], v[14:15], v[106:107]
	v_pk_fma_f32 v[44:45], v[44:45], v[206:207], v[108:109]
	v_pk_fma_f32 v[46:47], v[46:47], v[208:209], v[110:111]
	ds_read_b128 v[2:5], v0 offset:256
	ds_read_b128 v[8:11], v0 offset:288
	ds_read_b128 v[12:15], v0 offset:320
	ds_read_b128 v[206:209], v0 offset:352
	s_waitcnt vmcnt(16) lgkmcnt(0)
	v_pk_fma_f32 v[48:49], v[48:49], v[2:3], v[112:113]
	v_pk_fma_f32 v[50:51], v[50:51], v[4:5], v[114:115]
	v_pk_fma_f32 v[52:53], v[52:53], v[8:9], v[116:117]
	v_pk_fma_f32 v[54:55], v[54:55], v[10:11], v[118:119]
	v_pk_fma_f32 v[56:57], v[56:57], v[12:13], v[120:121]
	v_pk_fma_f32 v[58:59], v[58:59], v[14:15], v[122:123]
	v_pk_fma_f32 v[60:61], v[60:61], v[206:207], v[124:125]
	v_pk_fma_f32 v[62:63], v[62:63], v[208:209], v[126:127]
	ds_read_b128 v[2:5], v0 offset:384
	ds_read_b128 v[8:11], v0 offset:416
	ds_read_b128 v[12:15], v0 offset:448
	ds_read_b128 v[206:209], v0 offset:480
	s_waitcnt vmcnt(0) lgkmcnt(0)
	v_pk_fma_f32 v[64:65], v[64:65], v[2:3], v[128:129]
	v_pk_fma_f32 v[66:67], v[66:67], v[4:5], v[130:131]
	v_pk_fma_f32 v[68:69], v[68:69], v[8:9], v[132:133]
	v_pk_fma_f32 v[70:71], v[70:71], v[10:11], v[134:135]
	v_pk_fma_f32 v[72:73], v[72:73], v[12:13], v[136:137]
	v_pk_fma_f32 v[74:75], v[74:75], v[14:15], v[138:139]
	v_pk_fma_f32 v[76:77], v[76:77], v[206:207], v[140:141]
	v_pk_fma_f32 v[78:79], v[78:79], v[208:209], v[142:143]
	s_addk_i32 s21, 0x200
	s_cmp_eq_u32 s37, s5
	s_cbranch_scc0 .LBB0_287
